# nt hint also on the last-use xr/yg loads of the second RNN phase and the attention q-row loads
# baseline (speedup 1.0000x reference)
; #define SBAR() __builtin_amdgcn_sched_barrier(0)
; __device__ __forceinline__ void finishSM(f32x16& p0, f32x16& p1, float& l_reg, bf16x8& pa0, bf16x8& pa1, bf16x8& pa2, bf16x8& pa3) {
;     for (int r = 0; r < 16; ++r) p1[r] = __builtin_amdgcn_exp2f(p1[r]);
;     float ps = 0; for (int r = 0; r < 16; ++r) ps += p0[r]; for (int r = 0; r < 16; ++r) ps += p1[r];
;     { auto rr = __builtin_amdgcn_permlane32_swap(__float_as_uint(ps), __float_as_uint(ps), false, false);
;       ps = __uint_as_float(rr[0]) + __uint_as_float(rr[1]); }
;     l_reg += ps;
;     ...
;     PK4(p0, 0, pa0); PK4(p0, 8, pa1); PK4(p1, 0, pa2); PK4(p1, 8, pa3);
;     ...
; }
; template <int KB>
; __device__ __forceinline__ void qkt(f32x16& p0, f32x16& p1, const char* K_lds, int r32, int hi, const bf16x8* qr, const char* bp) {
;     ...
;     p0 = f32x16{}; p1 = f32x16{};
;     ...
;     { const f32x4 b0 = *(const f32x4*)(bp), b1 = *(const f32x4*)(bp + 32), b2 = *(const f32x4*)(bp + 64), b3 = *(const f32x4*)(bp + 96);
;       const f32x4 c0 = *(const f32x4*)(bp + 128), c1 = *(const f32x4*)(bp + 160), c2 = *(const f32x4*)(bp + 192), c3 = *(const f32x4*)(bp + 224);
; #pragma unroll
;       for (int e = 0; e < 4; ++e) { p0[e] = b0[e]; p0[4 + e] = b1[e]; p0[8 + e] = b2[e]; p0[12 + e] = b3[e]; p1[e] = c0[e]; p1[4 + e] = c1[e]; p1[8 + e] = c2[e]; p1[12 + e] = c3[e]; } }
;     ...
;     const char* kb[4];
; #pragma unroll
;     for (int dd = 0; dd < 4; ++dd) kb[dd] = K_lds + KB * SHM_K + KSWZ(r32, (dd * 16 + hi * 8) * 2);
; #pragma unroll
;     for (int d0 = 0; d0 < 8; ++d0) { const char* a = kb[d0 & 3] + (d0 >> 2) * 128;
;         bf16x8 b0 = *reinterpret_cast<const bf16x8*>(a);
;         bf16x8 b1 = *reinterpret_cast<const bf16x8*>(a + 32 * 256);
;         p0 = __builtin_amdgcn_mfma_f32_32x32x16_bf16(b0, qr[d0], p0, 0, 0, 0);
;         p1 = __builtin_amdgcn_mfma_f32_32x32x16_bf16(b1, qr[d0], p1, 0, 0, 0); }
; }
; template <int VB>
; __device__ __forceinline__ void pv_tile(f32x16* o, int vb0, bf16x8 pa0, bf16x8 pa1, bf16x8 pa2, bf16x8 pa3) {
;     ...
;     PV_D0(0); PV_D0(1); PV_D0(2); PV_D0(3);
; __device__ __forceinline__ void fox_block(unsigned char* ws, const BRef& cur, BRef& nxt, char* lds, Seam& S, volatile __attribute__((address_space(3))) unsigned* cnt) {
;     ...
;     { SLOAD_H((const bf16_t*)(ws + WS_KB) + nxt.kv, (const bf16_t*)(ws + WS_VB) + nxt.kv, kbn); SBAR();
;       const bf16_t* qp = q_lane_ptr(ws, nxt, wid, r32, hi);
; #pragma unroll
.LBB0_1658:
	s_mov_b32 s49, s25
	s_lshl_b64 s[10:11], s[48:49], 1
	s_add_u32 s10, s60, s10
	s_addc_u32 s11, s61, s11
	v_ashrrev_i32_e32 v123, 31, v122
	v_lshl_add_u64 v[122:123], v[122:123], 1, s[10:11]
	v_mov_b32_e32 v201, v195
	v_lshl_add_u64 v[122:123], v[122:123], 0, v[200:201]
	global_load_dwordx4 v[158:161], v[122:123], off nt
	global_load_dwordx4 v[154:157], v[122:123], off offset:32 nt
	global_load_dwordx4 v[150:153], v[122:123], off offset:64 nt
	global_load_dwordx4 v[146:149], v[122:123], off offset:96 nt
	global_load_dwordx4 v[142:145], v[122:123], off offset:128 nt
	global_load_dwordx4 v[138:141], v[122:123], off offset:160 nt
	global_load_dwordx4 v[134:137], v[122:123], off offset:192 nt
	global_load_dwordx4 v[130:133], v[122:123], off offset:224 nt
	v_exp_f32_e32 v182, v106
	v_add_f32_e32 v106, 0, v177
	v_add_f32_e32 v106, v179, v106
	v_add_f32_e32 v106, v175, v106
	v_add_f32_e32 v106, v178, v106
	v_add_f32_e32 v106, v174, v106
	v_add_f32_e32 v106, v176, v106
	v_add_f32_e32 v106, v172, v106
	v_add_f32_e32 v106, v173, v106
	v_add_f32_e32 v106, v129, v106
	v_add_f32_e32 v106, v171, v106
	v_add_f32_e32 v106, v128, v106
	v_add_f32_e32 v106, v170, v106
	v_exp_f32_e32 v120, v120
	v_add_f32_e32 v106, v125, v106
	v_exp_f32_e32 v121, v121
	v_add_f32_e32 v106, v127, v106
	v_exp_f32_e32 v118, v118
	v_add_f32_e32 v106, v124, v106
	v_exp_f32_e32 v119, v119
	v_add_f32_e32 v106, v126, v106
	v_exp_f32_e32 v122, v116
	v_add_f32_e32 v106, v120, v106
	v_exp_f32_e32 v123, v117
	v_add_f32_e32 v106, v121, v106
	v_exp_f32_e32 v180, v114
	v_add_f32_e32 v106, v118, v106
	v_exp_f32_e32 v181, v115
	v_add_f32_e32 v106, v119, v106
	v_add_f32_e32 v106, v122, v106
	v_exp_f32_e32 v107, v107
	v_add_f32_e32 v106, v123, v106
	v_exp_f32_e32 v183, v108
	v_add_f32_e32 v106, v180, v106
	v_exp_f32_e32 v184, v109
	v_add_f32_e32 v106, v181, v106
	v_exp_f32_e32 v185, v110
	v_add_f32_e32 v106, v182, v106
	v_exp_f32_e32 v186, v111
	v_add_f32_e32 v106, v107, v106
	v_exp_f32_e32 v187, v112
	v_add_f32_e32 v106, v183, v106
	v_exp_f32_e32 v188, v113
	v_add_f32_e32 v106, v184, v106
	v_add_f32_e32 v106, v185, v106
	v_add_f32_e32 v106, v186, v106
	v_add_f32_e32 v106, v187, v106
	v_add_f32_e32 v106, v188, v106
	v_mov_b32_e32 v108, v106
	s_nop 1
	v_permlane32_swap_b32_e32 v106, v108
	v_add_f32_e32 v106, v106, v108
	v_add_f32_e32 v106, v234, v106
	v_cvt_pk_bf16_f32 v108, v177, v179
	v_cvt_pk_bf16_f32 v109, v175, v178
	v_cvt_pk_bf16_f32 v110, v174, v176
	v_cvt_pk_bf16_f32 v111, v172, v173
	v_cvt_pk_bf16_f32 v112, v129, v171
	v_cvt_pk_bf16_f32 v113, v128, v170
	v_cvt_pk_bf16_f32 v114, v125, v127
	v_cvt_pk_bf16_f32 v115, v124, v126
	v_cvt_pk_bf16_f32 v116, v120, v121
	v_cvt_pk_bf16_f32 v117, v118, v119
	v_cvt_pk_bf16_f32 v118, v122, v123
	v_cvt_pk_bf16_f32 v119, v180, v181
	v_cvt_pk_bf16_f32 v120, v182, v107
	v_cvt_pk_bf16_f32 v121, v183, v184
	v_cvt_pk_bf16_f32 v122, v185, v186
	v_cvt_pk_bf16_f32 v123, v187, v188
	s_nop 0
	v_permlane32_swap_b32_e32 v108, v110
	v_permlane32_swap_b32_e32 v109, v111
	v_permlane32_swap_b32_e32 v112, v114
	v_permlane32_swap_b32_e32 v113, v115
	v_permlane32_swap_b32_e32 v116, v118
	v_permlane32_swap_b32_e32 v117, v119
	v_permlane32_swap_b32_e32 v120, v122
	v_permlane32_swap_b32_e32 v121, v123
	ds_read_b64_tr_b16 v[124:125], v224 offset:0
	ds_read_b64_tr_b16 v[126:127], v224 offset:0x800
	ds_read_b64_tr_b16 v[170:171], v224 offset:0x1000
	ds_read_b64_tr_b16 v[172:173], v224 offset:0x1800
	ds_read_b64_tr_b16 v[174:175], v224 offset:0x2000
	ds_read_b64_tr_b16 v[176:177], v224 offset:0x2800
	ds_read_b64_tr_b16 v[178:179], v224 offset:0x3000
	ds_read_b64_tr_b16 v[180:181], v224 offset:0x3800
	s_waitcnt lgkmcnt(0)
	s_nop 0
	v_mfma_f32_32x32x16_bf16 v[50:65], v[108:111], v[124:127], v[50:65]
	ds_read_b64_tr_b16 v[124:125], v224 offset:0x200
	ds_read_b64_tr_b16 v[126:127], v224 offset:0xa00
	v_mfma_f32_32x32x16_bf16 v[50:65], v[112:115], v[170:173], v[50:65]
	ds_read_b64_tr_b16 v[170:171], v224 offset:0x1200
	ds_read_b64_tr_b16 v[172:173], v224 offset:0x1a00
	v_mfma_f32_32x32x16_bf16 v[50:65], v[116:119], v[174:177], v[50:65]
	ds_read_b64_tr_b16 v[174:175], v224 offset:0x2200
	ds_read_b64_tr_b16 v[176:177], v224 offset:0x2a00
	ds_read_b64_tr_b16 v[182:183], v224 offset:0x3200
	ds_read_b64_tr_b16 v[184:185], v224 offset:0x3a00
	s_waitcnt lgkmcnt(0)
	v_mfma_f32_32x32x16_bf16 v[50:65], v[120:123], v[178:181], v[50:65]
	v_mfma_f32_32x32x16_bf16 v[34:49], v[108:111], v[124:127], v[34:49]
	ds_read_b64_tr_b16 v[124:125], v224 offset:0x400
	ds_read_b64_tr_b16 v[126:127], v224 offset:0xc00
	v_mfma_f32_32x32x16_bf16 v[34:49], v[112:115], v[170:173], v[34:49]
	ds_read_b64_tr_b16 v[170:171], v224 offset:0x1400
	ds_read_b64_tr_b16 v[172:173], v224 offset:0x1c00
	v_mfma_f32_32x32x16_bf16 v[34:49], v[116:119], v[174:177], v[34:49]
	ds_read_b64_tr_b16 v[174:175], v224 offset:0x2400
	ds_read_b64_tr_b16 v[176:177], v224 offset:0x2c00
	ds_read_b64_tr_b16 v[178:179], v224 offset:0x3400
	ds_read_b64_tr_b16 v[180:181], v224 offset:0x3c00
	s_waitcnt lgkmcnt(0)
	v_mfma_f32_32x32x16_bf16 v[34:49], v[120:123], v[182:185], v[34:49]
	v_mfma_f32_32x32x16_bf16 v[18:33], v[108:111], v[124:127], v[18:33]
	ds_read_b64_tr_b16 v[124:125], v224 offset:0x600
	ds_read_b64_tr_b16 v[126:127], v224 offset:0xe00
	v_mfma_f32_32x32x16_bf16 v[18:33], v[112:115], v[170:173], v[18:33]
	ds_read_b64_tr_b16 v[170:171], v224 offset:0x1600
	ds_read_b64_tr_b16 v[172:173], v224 offset:0x1e00
	v_mfma_f32_32x32x16_bf16 v[18:33], v[116:119], v[174:177], v[18:33]
	ds_read_b64_tr_b16 v[174:175], v224 offset:0x2600
	ds_read_b64_tr_b16 v[176:177], v224 offset:0x2e00
	ds_read_b64_tr_b16 v[182:183], v224 offset:0x3600
	ds_read_b64_tr_b16 v[184:185], v224 offset:0x3e00
	s_waitcnt lgkmcnt(0)
	v_mfma_f32_32x32x16_bf16 v[18:33], v[120:123], v[178:181], v[18:33]
	v_mfma_f32_32x32x16_bf16 v[2:17], v[108:111], v[124:127], v[2:17]
	s_andn2_b64 vcc, exec, s[64:65]
	v_mfma_f32_32x32x16_bf16 v[2:17], v[112:115], v[170:173], v[2:17]
	v_mfma_f32_32x32x16_bf16 v[2:17], v[116:119], v[174:177], v[2:17]
	v_mfma_f32_32x32x16_bf16 v[2:17], v[120:123], v[182:185], v[2:17]
	s_cbranch_vccnz .LBB0_1662
; __device__ __forceinline__ void mask_tile(f32x16& p0, f32x16& p1, int dq, unsigned W) {
;     const float NEG = -__builtin_inff();
; #pragma unroll
;     for (int r = 0; r < 16; ++r) {
;         const int c = (r & 3) + 8 * (r >> 2);
;         if ((unsigned)(dq - c) >= W) p0[r] = NEG;
;         if ((unsigned)(dq - c - 32) >= W) p1[r] = NEG;
;     }
; }
	s_lshl_b32 s10, s27, 6
	s_add_i32 s11, s10, -1
	s_cmp_le_i32 s11, s53
	s_cbranch_scc1 .LBB0_1661
	v_subrev_u32_e32 v107, s10, v221
	v_add_u32_e32 v108, 0xc0000040, v107
	v_cmp_lt_u32_e32 vcc, s77, v108
	v_add_u32_e32 v108, 0xc0000020, v107
	s_nop 0
	v_cndmask_b32_e32 v66, v215, v66, vcc
	v_cmp_lt_u32_e32 vcc, s77, v108
	v_add_u32_e32 v108, 0xc000003f, v107
	s_nop 0
	v_cndmask_b32_e32 v82, v215, v82, vcc
	v_cmp_lt_u32_e32 vcc, s77, v108
	v_add_u32_e32 v108, 0xc000001f, v107
	s_nop 0
	v_cndmask_b32_e32 v67, v215, v67, vcc
	v_cmp_lt_u32_e32 vcc, s77, v108
	v_add_u32_e32 v108, 0xc000003e, v107
	s_nop 0
	v_cndmask_b32_e32 v83, v215, v83, vcc
	v_cmp_lt_u32_e32 vcc, s77, v108
	v_add_u32_e32 v108, 0xc000001e, v107
	s_nop 0
	v_cndmask_b32_e32 v68, v215, v68, vcc
	v_cmp_lt_u32_e32 vcc, s77, v108
	v_add_u32_e32 v108, 0xc000003d, v107
	s_nop 0
	v_cndmask_b32_e32 v84, v215, v84, vcc
	v_cmp_lt_u32_e32 vcc, s77, v108
	v_add_u32_e32 v108, 0xc000001d, v107
	s_nop 0
	v_cndmask_b32_e32 v69, v215, v69, vcc
	v_cmp_lt_u32_e32 vcc, s77, v108
	v_add_u32_e32 v108, 0xc0000038, v107
	s_nop 0
	v_cndmask_b32_e32 v85, v215, v85, vcc
	v_cmp_lt_u32_e32 vcc, s77, v108
	v_add_u32_e32 v108, 0xc0000018, v107
	s_nop 0
	v_cndmask_b32_e32 v70, v215, v70, vcc
	v_cmp_lt_u32_e32 vcc, s77, v108
	v_add_u32_e32 v108, 0xc0000037, v107
	s_nop 0
	v_cndmask_b32_e32 v86, v215, v86, vcc
	v_cmp_lt_u32_e32 vcc, s77, v108
	v_add_u32_e32 v108, 0xc0000017, v107
	s_nop 0
	v_cndmask_b32_e32 v71, v215, v71, vcc
	v_cmp_lt_u32_e32 vcc, s77, v108
	v_add_u32_e32 v108, 0xc0000036, v107
	s_nop 0
	v_cndmask_b32_e32 v87, v215, v87, vcc
	v_cmp_lt_u32_e32 vcc, s77, v108
	v_add_u32_e32 v108, 0xc0000016, v107
	s_nop 0
	v_cndmask_b32_e32 v72, v215, v72, vcc
	v_cmp_lt_u32_e32 vcc, s77, v108
	v_add_u32_e32 v108, 0xc0000035, v107
	s_nop 0
	v_cndmask_b32_e32 v88, v215, v88, vcc
	v_cmp_lt_u32_e32 vcc, s77, v108
	v_add_u32_e32 v108, 0xc0000015, v107
	s_nop 0
	v_cndmask_b32_e32 v73, v215, v73, vcc
	v_cmp_lt_u32_e32 vcc, s77, v108
	v_add_u32_e32 v108, 0xc0000030, v107
	s_nop 0
	v_cndmask_b32_e32 v89, v215, v89, vcc
	v_cmp_lt_u32_e32 vcc, s77, v108
	v_add_u32_e32 v108, 0xc0000010, v107
	s_nop 0
	v_cndmask_b32_e32 v74, v215, v74, vcc
	v_cmp_lt_u32_e32 vcc, s77, v108
	v_add_u32_e32 v108, 0xc000002f, v107
	s_nop 0
	v_cndmask_b32_e32 v90, v215, v90, vcc
	v_cmp_lt_u32_e32 vcc, s77, v108
	v_add_u32_e32 v108, 0xc000000f, v107
	s_nop 0
	v_cndmask_b32_e32 v75, v215, v75, vcc
	v_cmp_lt_u32_e32 vcc, s77, v108
	v_add_u32_e32 v108, 0xc000002e, v107
	s_nop 0
	v_cndmask_b32_e32 v91, v215, v91, vcc
	v_cmp_lt_u32_e32 vcc, s77, v108
	v_add_u32_e32 v108, 0xc000000e, v107
	s_nop 0
	v_cndmask_b32_e32 v76, v215, v76, vcc
	v_cmp_lt_u32_e32 vcc, s77, v108
	v_add_u32_e32 v108, 0xc000002d, v107
	s_nop 0
	v_cndmask_b32_e32 v92, v215, v92, vcc
	v_cmp_lt_u32_e32 vcc, s77, v108
	v_add_u32_e32 v108, 0xc000000d, v107
	s_nop 0
	v_cndmask_b32_e32 v77, v215, v77, vcc
	v_cmp_lt_u32_e32 vcc, s77, v108
	v_add_u32_e32 v108, 0xc0000028, v107
	s_nop 0
	v_cndmask_b32_e32 v93, v215, v93, vcc
	v_cmp_lt_u32_e32 vcc, s77, v108
	v_add_u32_e32 v108, 0xc0000008, v107
	s_nop 0
	v_cndmask_b32_e32 v78, v215, v78, vcc
	v_cmp_lt_u32_e32 vcc, s77, v108
	v_add_u32_e32 v108, 0xc0000027, v107
	s_nop 0
	v_cndmask_b32_e32 v94, v215, v94, vcc
	v_cmp_lt_u32_e32 vcc, s77, v108
	v_add_u32_e32 v108, 0xc0000007, v107
	s_nop 0
	v_cndmask_b32_e32 v79, v215, v79, vcc
	v_cmp_lt_u32_e32 vcc, s77, v108
	v_add_u32_e32 v108, 0xc0000026, v107
	s_nop 0
	v_cndmask_b32_e32 v95, v215, v95, vcc
	v_cmp_lt_u32_e32 vcc, s77, v108
	v_add_u32_e32 v108, 0xc0000006, v107
	s_nop 0
	v_cndmask_b32_e32 v80, v215, v80, vcc
	v_cmp_lt_u32_e32 vcc, s77, v108
	v_add_u32_e32 v108, 0xc0000025, v107
	v_add_u32_e32 v107, 0xc0000005, v107
	v_cndmask_b32_e32 v96, v215, v96, vcc
	v_cmp_lt_u32_e32 vcc, s77, v108
	s_nop 1
	v_cndmask_b32_e32 v81, v215, v81, vcc
	v_cmp_lt_u32_e32 vcc, s77, v107
	s_nop 1
	v_cndmask_b32_e32 v97, v215, v97, vcc

; #define GAS __attribute__((address_space(1)))
; #define LAS __attribute__((address_space(3)))
; template <int MODE> __device__ __forceinline__ void rnn_issue(const RnnP& P, RnnPre& pre, int tid, int R0, int n, int samp, int c) {
;     const bool hist_ok = (!samp) && (c > 0);
; #pragma unroll
;     for (int k = 0; k < 3; ++k) { const int i = tid + k * NTHR; pre.x[k] = (v4u){0u, 0u, 0u, 0u};
;         if (i < 67 * 16) { const int j = i >> 4, cc = i & 15; if (j >= 3 || hist_ok) pre.x[k] = *(const GAS v4u*)(P.XR + (size_t)(R0 - 3 + j) * 2048 + n * 128 + cc * 8); } }
;     if (MODE == 1) {
; #pragma unroll
;         for (int k = 0; k < 2; ++k) { const int i = tid + k * NTHR, j = i >> 4, cc = i & 15; pre.y[k] = *(const GAS v4u*)(P.YG + (size_t)(R0 + j) * 2048 + n * 128 + cc * 8); } }
; }
; template <int MODE> __device__ __forceinline__ void rnn_decode(int u, int& R0, int& n, int& samp, int& c) {
;     n = u & 15;
;     if (MODE == 1 && u < 64) { samp = 1; c = 0; R0 = 64 * (u >> 4); }
;     else { const int v = MODE == 1 ? u - 64 : u; samp = 0; c = v >> 4; R0 = ROWP + 64 * c; }
; }
; template <int MODE>
; __device__ __forceinline__ void rnn_phase(const RnnP& P, LAS unsigned char* lds, int G, int bid, int nunits) {
;     int tid = threadIdx.x; asm volatile("" : "+v"(tid));
;     const int lane = tid & 63, w = __builtin_amdgcn_readfirstlane(tid >> 6), ch = tid & 127, rg = tid >> 7;
;     LAS float* XRF = (LAS float*)(lds + R_XRF); LAS bf16* YGS = (LAS bf16*)(lds + R_YGS); LAS bf16* XCB = (LAS bf16*)(lds + R_XCB);
;     LAS float* GT = (LAS float*)(lds + R_GT); LAS float* CAR = (LAS float*)(lds + R_CAR); LAS float* SSW = (LAS float*)(lds + R_SSW);
;     const int gate = w >> 2, cb = 32 * (w & 3), jj = lane & 15, q = lane >> 4;
;     int u = bid; if (u >= nunits) return;
;     int R0, n, samp, c; rnn_decode<MODE>(u, R0, n, samp, c);
;     RnnPre pre; rnn_issue<MODE>(P, pre, tid, R0, n, samp, c);
.LBB0_2288:
	s_or_b64 exec, exec, s[6:7]
	s_mov_b64 s[6:7], s[96:97]
	s_waitcnt vmcnt(0)
	v_mov_b32_e32 v67, v0
	s_waitcnt lgkmcnt(0)
	s_barrier
	s_cmpk_lt_i32 s2, 0x1050
	s_nop 0
	v_readfirstlane_b32 s20, v67
	s_cbranch_scc0 .LBB0_2353
	s_load_dwordx4 s[40:43], s[6:7], 0xe0
	s_load_dwordx4 s[48:51], s[6:7], 0x28
	s_load_dwordx4 s[52:55], s[6:7], 0x60
	s_load_dwordx2 s[80:81], s[6:7], 0x78
	s_load_dwordx4 s[44:47], s[6:7], 0x88
	s_waitcnt lgkmcnt(0)
	s_add_u32 s64, s42, 0x2cd00000
	s_addc_u32 s65, s43, 0
	s_sub_i32 s0, s2, 64
	s_lshr_b32 s6, s0, 4
	s_lshl_b32 s0, s6, 6
	s_add_i32 s7, s0, 0x100
	s_lshl_b32 s0, s2, 2
	s_and_b32 s8, s0, 0xffffffc0
	s_cmp_gt_i32 s2, 63
	s_cselect_b64 s[12:13], -1, 0
	s_and_b64 s[0:1], s[12:13], exec
	s_cselect_b32 s70, s6, 0
	s_cselect_b32 s0, s7, s8
	s_cmp_lg_u32 s70, 0
	v_mov_b32_e32 v6, 0
	s_cselect_b64 s[6:7], -1, 0
	v_mov_b32_e32 v7, v6
	s_and_b64 s[14:15], s[12:13], s[6:7]
	v_lshlrev_b32_e32 v24, 3, v67
	s_movk_i32 s6, 0x430
	v_mov_b32_e32 v8, v6
	v_mov_b32_e32 v9, v6
	v_mov_b64_e32 v[2:3], v[6:7]
	s_add_i32 s1, s0, -3
	v_and_b32_e32 v25, 0x78, v24
	v_cmp_gt_i32_e64 s[6:7], s6, v67
	v_ashrrev_i32_e32 v120, 4, v67
	v_mov_b64_e32 v[4:5], v[8:9]
	s_and_saveexec_b64 s[8:9], s[6:7]
	s_cbranch_execz .LBB0_2293
	v_cmp_lt_i32_e32 vcc, 2, v120
	s_or_b64 s[18:19], vcc, s[14:15]
	s_mov_b32 s17, 0
	v_mov_b32_e32 v2, v6
	v_mov_b32_e32 v3, v6
	v_mov_b32_e32 v4, v6
	v_mov_b32_e32 v5, v6
	s_and_saveexec_b64 s[10:11], s[18:19]
	s_cbranch_execz .LBB0_2292
	v_add_u32_e32 v2, s1, v120
	v_ashrrev_i32_e32 v3, 31, v2
	v_lshlrev_b64 v[2:3], 12, v[2:3]
	v_lshl_add_u64 v[2:3], s[64:65], 0, v[2:3]
	s_lshl_b32 s16, s5, 1
	v_lshl_add_u64 v[2:3], v[2:3], 0, s[16:17]
	v_lshlrev_b32_e32 v4, 1, v25
	v_mov_b32_e32 v5, 0
	v_lshl_add_u64 v[2:3], v[2:3], 0, v[4:5]
	global_load_dwordx4 v[2:5], v[2:3], off nt

; #define GAS __attribute__((address_space(1)))
; template <int MODE> __device__ __forceinline__ void rnn_issue(const RnnP& P, RnnPre& pre, int tid, int R0, int n, int samp, int c) {
;     const bool hist_ok = (!samp) && (c > 0);
; #pragma unroll
;     for (int k = 0; k < 3; ++k) { const int i = tid + k * NTHR; pre.x[k] = (v4u){0u, 0u, 0u, 0u};
;         if (i < 67 * 16) { const int j = i >> 4, cc = i & 15; if (j >= 3 || hist_ok) pre.x[k] = *(const GAS v4u*)(P.XR + (size_t)(R0 - 3 + j) * 2048 + n * 128 + cc * 8); } }
.LBB0_2293:
	s_or_b64 exec, exec, s[8:9]
	v_add_u32_e32 v26, 0x200, v67
	s_movk_i32 s8, 0x230
	v_cmp_gt_i32_e64 s[8:9], s8, v67
	v_ashrrev_i32_e32 v121, 4, v26
	s_and_saveexec_b64 s[10:11], s[8:9]
	s_cbranch_execz .LBB0_2297
	v_cmp_lt_i32_e32 vcc, 2, v121
	v_mov_b32_e32 v6, 0
	s_or_b64 s[22:23], vcc, s[14:15]
	s_mov_b32 s19, 0
	v_mov_b32_e32 v7, v6
	v_mov_b32_e32 v8, v6
	v_mov_b32_e32 v9, v6
	s_and_saveexec_b64 s[16:17], s[22:23]
	s_cbranch_execz .LBB0_2296
	v_add_u32_e32 v8, s1, v121
	v_ashrrev_i32_e32 v9, 31, v8
	v_lshlrev_b64 v[8:9], 12, v[8:9]
	v_lshl_add_u64 v[8:9], s[64:65], 0, v[8:9]
	s_lshl_b32 s18, s5, 1
	v_lshl_add_u64 v[8:9], v[8:9], 0, s[18:19]
	v_lshlrev_b32_e32 v10, 1, v25
	v_mov_b32_e32 v11, v6
	v_lshl_add_u64 v[6:7], v[8:9], 0, v[10:11]
	global_load_dwordx4 v[6:9], v[6:7], off nt

; #define GAS __attribute__((address_space(1)))
; template <int MODE> __device__ __forceinline__ void rnn_issue(const RnnP& P, RnnPre& pre, int tid, int R0, int n, int samp, int c) {
;     const bool hist_ok = (!samp) && (c > 0);
; #pragma unroll
;     for (int k = 0; k < 3; ++k) { const int i = tid + k * NTHR; pre.x[k] = (v4u){0u, 0u, 0u, 0u};
;         if (i < 67 * 16) { const int j = i >> 4, cc = i & 15; if (j >= 3 || hist_ok) pre.x[k] = *(const GAS v4u*)(P.XR + (size_t)(R0 - 3 + j) * 2048 + n * 128 + cc * 8); } }
.LBB0_2297:
	s_or_b64 exec, exec, s[10:11]
	v_cmp_gt_i32_e64 s[10:11], 48, v67
	v_cmp_lt_i32_e32 vcc, 47, v67
	v_add_u32_e32 v27, 0x400, v67
	s_and_saveexec_b64 s[16:17], vcc
	s_xor_b64 s[16:17], exec, s[16:17]
	v_lshrrev_b32_e32 v122, 4, v27
	s_or_saveexec_b64 s[16:17], s[16:17]
	v_mov_b32_e32 v10, 0
	v_mov_b32_e32 v12, v10
	v_mov_b32_e32 v13, v10
	v_mov_b32_e32 v11, v10
	v_mov_b64_e32 v[14:15], v[12:13]
	s_mov_b32 s67, 0
	v_mov_b64_e32 v[12:13], v[10:11]
	s_xor_b64 exec, exec, s[16:17]
	s_cbranch_execz .LBB0_2303
	v_ashrrev_i32_e32 v122, 4, v27
	v_cmp_lt_i32_e32 vcc, 2, v122
	v_mov_b32_e32 v12, 0
	s_or_b64 s[18:19], vcc, s[14:15]
	v_mov_b32_e32 v13, v12
	v_mov_b32_e32 v14, v12
	v_mov_b32_e32 v15, v12
	s_and_saveexec_b64 s[14:15], s[18:19]
	s_cbranch_execz .LBB0_2302
	v_add_u32_e32 v14, s1, v122
	v_ashrrev_i32_e32 v15, 31, v14
	v_lshlrev_b64 v[14:15], 12, v[14:15]
	v_lshl_add_u64 v[14:15], s[64:65], 0, v[14:15]
	s_lshl_b32 s66, s5, 1
	v_lshl_add_u64 v[14:15], v[14:15], 0, s[66:67]
	v_lshlrev_b32_e32 v16, 1, v25
	v_mov_b32_e32 v17, v12
	v_lshl_add_u64 v[12:13], v[14:15], 0, v[16:17]
	global_load_dwordx4 v[12:15], v[12:13], off nt

; #define GAS __attribute__((address_space(1)))
; #define LAS __attribute__((address_space(3)))
; template <int MODE> __device__ __forceinline__ void rnn_issue(const RnnP& P, RnnPre& pre, int tid, int R0, int n, int samp, int c) {
;     ...
;     if (MODE == 1) {
; #pragma unroll
;         for (int k = 0; k < 2; ++k) { const int i = tid + k * NTHR, j = i >> 4, cc = i & 15; pre.y[k] = *(const GAS v4u*)(P.YG + (size_t)(R0 + j) * 2048 + n * 128 + cc * 8); } }
; }
; template <int MODE> __device__ __forceinline__ void rnn_decode(int u, int& R0, int& n, int& samp, int& c) {
;     n = u & 15;
;     if (MODE == 1 && u < 64) { samp = 1; c = 0; R0 = 64 * (u >> 4); }
;     else { const int v = MODE == 1 ? u - 64 : u; samp = 0; c = v >> 4; R0 = ROWP + 64 * c; }
; }
; template <int MODE>
; __device__ __forceinline__ void rnn_phase(const RnnP& P, LAS unsigned char* lds, int G, int bid, int nunits) {
;     int tid = threadIdx.x; asm volatile("" : "+v"(tid));
;     const int lane = tid & 63, w = __builtin_amdgcn_readfirstlane(tid >> 6), ch = tid & 127, rg = tid >> 7;
;     LAS float* XRF = (LAS float*)(lds + R_XRF); LAS bf16* YGS = (LAS bf16*)(lds + R_YGS); LAS bf16* XCB = (LAS bf16*)(lds + R_XCB);
;     LAS float* GT = (LAS float*)(lds + R_GT); LAS float* CAR = (LAS float*)(lds + R_CAR); LAS float* SSW = (LAS float*)(lds + R_SSW);
;     const int gate = w >> 2, cb = 32 * (w & 3), jj = lane & 15, q = lane >> 4;
;     int u = bid; if (u >= nunits) return;
;     int R0, n, samp, c; rnn_decode<MODE>(u, R0, n, samp, c);
;     RnnPre pre; rnn_issue<MODE>(P, pre, tid, R0, n, samp, c);
;     int n_loaded = -1; bf16x8 Bf[2][4]; float nb0 = 0.f, nb1 = 0.f, w0 = 0.f, w1 = 0.f, w2 = 0.f, w3 = 0.f, bc = 0.f, c2s = 0.f;
.LBB0_2303:
	s_or_b64 exec, exec, s[16:17]
	s_xor_b64 s[12:13], s[12:13], -1
	s_add_u32 s68, s42, 0x30f00000
	s_addc_u32 s69, s43, 0
	s_add_u32 s72, s42, 0x3d500000
	s_addc_u32 s73, s43, 0
	s_add_u32 s1, s42, 0x1000000
	s_addc_u32 s57, s43, 0
	s_add_u32 s74, s42, 0x1300000
	s_addc_u32 s75, s43, 0
	s_add_u32 s76, s40, 0x14510400
	v_add_u32_e32 v16, s0, v120
	v_add_u32_e32 v18, s0, v121
	s_addc_u32 s77, s41, 0
	v_ashrrev_i32_e32 v17, 31, v16
	v_ashrrev_i32_e32 v19, 31, v18
	s_add_u32 s78, s40, 0x14634400
	v_lshlrev_b64 v[16:17], 12, v[16:17]
	v_lshlrev_b64 v[18:19], 12, v[18:19]
	s_addc_u32 s79, s41, 0
	v_lshl_add_u64 v[16:17], s[68:69], 0, v[16:17]
	s_lshl_b32 s66, s5, 1
	v_lshl_add_u64 v[18:19], s[68:69], 0, v[18:19]
	v_lshl_add_u64 v[16:17], v[16:17], 0, s[66:67]
	v_lshlrev_b32_e32 v56, 1, v25
	v_mov_b32_e32 v57, v10
	v_lshl_add_u64 v[18:19], v[18:19], 0, s[66:67]
	v_lshl_add_u64 v[16:17], v[16:17], 0, v[56:57]
	v_lshl_add_u64 v[20:21], v[18:19], 0, v[56:57]
	global_load_dwordx4 v[16:19], v[16:17], off nt
	s_nop 0
	global_load_dwordx4 v[20:23], v[20:21], off nt
	v_cndmask_b32_e64 v149, 0, 1, s[12:13]
	v_and_b32_e32 v1, 63, v67
	v_and_b32_e32 v123, 0x7f, v67
	s_lshr_b32 s13, s20, 2
	v_lshlrev_b32_e32 v29, 2, v123
	s_add_i32 s5, 0, 0x22200
	s_and_b32 s18, s13, 0xfffffc0
	s_and_b32 s13, s20, 0xffffffc0
	v_and_b32_e32 v41, 8, v67
	v_cmp_gt_u32_e64 s[28:29], 16, v1
	v_and_b32_e32 v1, 3, v67
	v_and_b32_e32 v11, 15, v67
	v_add_u32_e32 v33, 0, v29
	v_lshlrev_b32_e32 v28, 1, v123
	s_add_i32 s30, s5, s13
	v_cmp_eq_u32_e64 s[26:27], 0, v41
	v_lshlrev_b32_e32 v1, 2, v1
	v_lshlrev_b32_e32 v41, 1, v41
	v_sub_u32_e32 v34, v33, v28
	v_lshlrev_b32_e32 v28, 2, v11
	v_add3_u32 v1, s30, v1, v41
	v_and_b32_e32 v41, 0xffffff80, v24
	v_or_b32_e32 v24, v41, v28
	v_add3_u32 v128, s5, v24, 64
	v_lshlrev_b32_e32 v24, 5, v26
	v_lshl_add_u32 v25, v25, 2, 0
	v_and_b32_e32 v24, 0xfffffe00, v24
	v_add_u32_e32 v130, v25, v24
	v_lshlrev_b32_e32 v24, 5, v27
	v_ashrrev_i32_e32 v124, 7, v67
	s_lshr_b32 s12, s20, 1
	v_add_u32_e32 v35, s5, v28
	v_and_b32_e32 v24, 0xfffffe00, v24
	s_movk_i32 s5, 0x1100
	s_and_b32 s12, s12, 0x60
	v_lshrrev_b32_e32 v31, 2, v67
	v_add_u32_e32 v131, v25, v24
	v_mul_lo_u32 v42, v124, s5
	v_lshl_or_b32 v24, v124, 4, 2
	s_movk_i32 s5, 0x110
	s_add_i32 s34, 0, 0x10a00
	s_lshl_b32 s60, s12, 2
	v_and_or_b32 v31, v31, 12, s18
	v_mul_lo_u32 v43, v24, s5
	s_movk_i32 s5, 0x210
	s_add_i32 s35, s34, s60
	v_or_b32_e32 v36, s12, v11
	v_mul_u32_u24_e32 v44, 0x110, v11
	v_mul_lo_u32 v11, v31, s5
	v_add3_u32 v133, s35, v11, v28
	s_movk_i32 s35, 0x2100
	s_add_i32 s19, 0, 0x21200
	v_mul_lo_u32 v11, v124, s35
	s_cmpk_lt_u32 s20, 0x100
	v_add3_u32 v141, s34, v11, v29
	v_mul_lo_u32 v11, v24, s5
	s_mov_b32 s5, 0x180000
	s_cselect_b32 s5, s5, 0x200000
	v_and_b32_e32 v40, 1, v67
	s_cselect_b32 s45, s81, s45
	s_cselect_b32 s44, s80, s44
	s_add_u32 s40, s42, s5
	v_and_b32_e32 v30, 48, v67
	v_cmp_eq_u32_e64 s[20:21], 0, v40
	v_and_b32_e32 v40, 2, v67
	s_addc_u32 s41, s43, 0
	v_mov_b32_e32 v31, v10
	v_sub_u32_e32 v32, v25, v56
	v_and_b32_e32 v39, 0x3fffff80, v67
	v_add_u32_e32 v126, s19, v29
	v_cmp_eq_u32_e64 s[22:23], 0, v40
	v_and_b32_e32 v40, 4, v67
	v_lshl_add_u32 v129, v41, 2, v25
	v_lshl_add_u64 v[24:25], s[40:41], 0, v[30:31]
	s_add_u32 s40, s44, s60
	v_lshlrev_b32_e32 v37, 13, v124
	v_add_u32_e32 v38, 0, v30
	v_lshl_add_u32 v127, v39, 2, v126
	v_lshlrev_b32_e32 v39, 12, v124
	s_movk_i32 s18, 0x80
	v_cmp_eq_u32_e64 s[24:25], 0, v40
	v_lshlrev_b32_e32 v40, 3, v40
	v_add3_u32 v142, s34, v11, v29
	v_lshlrev_b32_e32 v45, 8, v120
	v_lshlrev_b32_e32 v46, 8, v121
	v_lshlrev_b32_e32 v26, 8, v36
	v_mov_b32_e32 v27, v10
	s_addc_u32 s41, s45, 0
	v_mov_b32_e32 v29, v10
	s_add_i32 s5, s2, s33
	v_mov_b32_e32 v11, v10
	s_mov_b32 s80, 0xc138aa3b
	v_cmp_lt_i32_e64 s[12:13], 2, v120
	v_cmp_lt_i32_e64 s[14:15], 2, v121
	v_cmp_lt_i32_e64 s[16:17], 2, v122
	v_lshl_add_u32 v125, v67, 2, s19
	v_cmp_gt_u32_e64 s[18:19], s18, v67
	v_cmp_gt_i32_e64 s[30:31], 64, v67
	v_lshl_add_u32 v132, v41, 1, v32
	v_add_u32_e32 v134, 0x420, v133
	v_add_u32_e32 v135, 0x2100, v133
	v_add_u32_e32 v136, 0x2520, v133
	v_add_u32_e32 v137, 0x4200, v133
	v_add_u32_e32 v138, 0x4620, v133
	v_add_u32_e32 v139, 0x6300, v133
	v_add_u32_e32 v140, 0x6720, v133
	v_add_u32_e32 v143, 0x420, v142
	v_add_u32_e32 v144, 0x840, v142
	v_add_u32_e32 v145, 0xc60, v142
	v_add_u32_e32 v146, 0x1080, v142
	v_add_u32_e32 v147, 0x14a0, v142
	v_add_u32_e32 v148, 0x18c0, v142
	v_cmp_lt_i32_e64 s[34:35], 0, v124
	v_cmp_lt_i32_e64 s[36:37], 1, v124
	v_cmp_lt_i32_e64 s[38:39], 2, v124
	v_lshl_add_u64 v[58:59], v[24:25], 0, v[26:27]
	v_lshl_add_u64 v[60:61], s[40:41], 0, v[28:29]
	s_lshl_b32 s5, s5, 2
	s_lshl_b32 s60, s33, 2
	s_mov_b32 s82, -1
	s_mov_b32 s81, 0xbfb8aa3b
	v_mov_b32_e32 v150, 0x3ecc95a3
	v_add_u32_e32 v151, v34, v42
	v_add_u32_e32 v152, v34, v43
	v_add_u32_e32 v153, v38, v44
	s_mov_b32 s84, 0x3fb8aa3b
	v_add_u32_e32 v154, v34, v39
	s_mov_b32 s86, 0x3dd2d3e5
	v_add_u32_e32 v155, v1, v40
	v_add_u32_e32 v156, v35, v41
	v_add_u32_e32 v157, v32, v45
	v_add_u32_e32 v158, v32, v46
	v_mov_b32_e32 v62, 0x3f317218
	v_mov_b32_e32 v159, 0x7f800000
	v_mov_b32_e32 v160, 0x7fc00000
	v_mov_b32_e32 v161, 0xff800000
	v_add_u32_e32 v162, v33, v37
	v_mbcnt_hi_u32_b32 v163, -1, v188
	v_mov_b32_e32 v164, 0
	v_mov_b32_e32 v165, 0
	v_mov_b32_e32 v166, 0
	v_mov_b32_e32 v167, 0
	v_mov_b32_e32 v168, 0
	v_mov_b32_e32 v66, 0
	s_mov_b32 s61, s2
	v_mov_b64_e32 v[68:69], v[10:11]
	s_branch .LBB0_2305

; #define GAS __attribute__((address_space(1)))
; template <int MODE> __device__ __forceinline__ void rnn_issue(const RnnP& P, RnnPre& pre, int tid, int R0, int n, int samp, int c) {
;     const bool hist_ok = (!samp) && (c > 0);
; #pragma unroll
;     for (int k = 0; k < 3; ++k) { const int i = tid + k * NTHR; pre.x[k] = (v4u){0u, 0u, 0u, 0u};
;         if (i < 67 * 16) { const int j = i >> 4, cc = i & 15; if (j >= 3 || hist_ok) pre.x[k] = *(const GAS v4u*)(P.XR + (size_t)(R0 - 3 + j) * 2048 + n * 128 + cc * 8); } }
;     if (MODE == 1) {
; #pragma unroll
;         for (int k = 0; k < 2; ++k) { const int i = tid + k * NTHR, j = i >> 4, cc = i & 15; pre.y[k] = *(const GAS v4u*)(P.YG + (size_t)(R0 + j) * 2048 + n * 128 + cc * 8); } }
; }
; template <int MODE>
; __device__ __forceinline__ void rnn_phase(const RnnP& P, LAS unsigned char* lds, int G, int bid, int nunits) {
;     ...
;         const int un = u + G; const bool has_next = un < nunits;
;         int R0n = R0, nn = n, sampn = samp, cn = c;
;         if (has_next) { rnn_decode<MODE>(un, R0n, nn, sampn, cn); rnn_issue<MODE>(P, pre, tid, R0n, nn, sampn, cn); }
.LBB0_2317:
	s_and_b32 s4, s61, 15
	s_cmp_lg_u32 s63, 0
	s_cselect_b64 s[92:93], -1, 0
	s_and_b64 s[40:41], s[40:41], s[92:93]
	v_mov_b32_e32 v11, v10
	s_or_b64 s[92:93], s[12:13], s[40:41]
	v_mov_b32_e32 v12, v10
	v_mov_b32_e32 v13, v10
	v_mov_b64_e32 v[2:3], v[10:11]
	s_add_i32 s85, s62, -3
	s_lshl_b32 s83, s4, 7
	s_and_b64 s[94:95], s[6:7], s[92:93]
	v_mov_b64_e32 v[4:5], v[12:13]
	s_and_saveexec_b64 s[92:93], s[94:95]
	s_cbranch_execz .LBB0_2319
	v_add_u32_e32 v2, s85, v120
	v_ashrrev_i32_e32 v3, 31, v2
	v_lshlrev_b64 v[2:3], 12, v[2:3]
	v_lshl_add_u64 v[2:3], s[64:65], 0, v[2:3]
	s_lshl_b32 s66, s83, 1
	v_lshl_add_u64 v[2:3], v[2:3], 0, s[66:67]
	v_mov_b32_e32 v57, v10
	v_lshl_add_u64 v[2:3], v[2:3], 0, v[56:57]
	global_load_dwordx4 v[2:5], v[2:3], off nt
.LBB0_2319:
	s_or_b64 exec, exec, s[92:93]
	s_or_b64 s[92:93], s[14:15], s[40:41]
	v_mov_b64_e32 v[6:7], v[10:11]
	s_and_b64 s[94:95], s[8:9], s[92:93]
	v_mov_b64_e32 v[8:9], v[12:13]
	s_and_saveexec_b64 s[92:93], s[94:95]
	s_cbranch_execz .LBB0_2321
	v_add_u32_e32 v6, s85, v121
	v_ashrrev_i32_e32 v7, 31, v6
	v_lshlrev_b64 v[6:7], 12, v[6:7]
	v_lshl_add_u64 v[6:7], s[64:65], 0, v[6:7]
	s_lshl_b32 s66, s83, 1
	v_lshl_add_u64 v[6:7], v[6:7], 0, s[66:67]
	v_mov_b32_e32 v57, v10
	v_lshl_add_u64 v[6:7], v[6:7], 0, v[56:57]
	global_load_dwordx4 v[6:9], v[6:7], off nt
.LBB0_2321:
	s_or_b64 exec, exec, s[92:93]
	v_mov_b32_e32 v12, v10
	v_mov_b32_e32 v13, v10
	s_or_b64 s[40:41], s[16:17], s[40:41]
	v_mov_b32_e32 v11, v10
	v_mov_b64_e32 v[14:15], v[12:13]
	s_and_b64 s[92:93], s[10:11], s[40:41]
	v_mov_b64_e32 v[12:13], v[10:11]
	s_and_saveexec_b64 s[40:41], s[92:93]
	s_cbranch_execz .LBB0_2323
	v_add_u32_e32 v12, s85, v122
	v_ashrrev_i32_e32 v13, 31, v12
	v_lshlrev_b64 v[12:13], 12, v[12:13]
	v_lshl_add_u64 v[12:13], s[64:65], 0, v[12:13]
	s_lshl_b32 s66, s83, 1
	v_lshl_add_u64 v[12:13], v[12:13], 0, s[66:67]
	v_mov_b32_e32 v57, v10
	v_lshl_add_u64 v[12:13], v[12:13], 0, v[56:57]
	global_load_dwordx4 v[12:15], v[12:13], off nt
.LBB0_2323:
	s_or_b64 exec, exec, s[40:41]
	v_add_u32_e32 v16, s62, v120
	v_add_u32_e32 v18, s62, v121
	v_ashrrev_i32_e32 v17, 31, v16
	v_ashrrev_i32_e32 v19, 31, v18
	v_lshlrev_b64 v[16:17], 12, v[16:17]
	v_lshlrev_b64 v[18:19], 12, v[18:19]
	v_lshl_add_u64 v[16:17], s[68:69], 0, v[16:17]
	s_lshl_b32 s66, s83, 1
	v_lshl_add_u64 v[18:19], s[68:69], 0, v[18:19]
	v_lshl_add_u64 v[16:17], v[16:17], 0, s[66:67]
	v_mov_b32_e32 v57, v10
	v_lshl_add_u64 v[18:19], v[18:19], 0, s[66:67]
	v_lshl_add_u64 v[16:17], v[16:17], 0, v[56:57]
	v_lshl_add_u64 v[20:21], v[18:19], 0, v[56:57]
	global_load_dwordx4 v[16:19], v[16:17], off nt
	s_nop 0
	global_load_dwordx4 v[20:23], v[20:21], off nt
	v_mov_b32_e32 v149, s71
